# K-loop handoff: s_setprio 1 moved before the pre-MFMA barrier, s_setprio 0 after the post-MFMA barrier, redundant lgkmcnt wait and mid-block prio toggles removed
# baseline (speedup 1.0000x reference)
.LBB0_159:
	s_add_u32 s0, s22, 0xfff80080
	s_addc_u32 s1, s23, -1
	s_add_i32 s51, 0, 0x10000
	s_cmp_eq_u32 s50, 28
	s_cselect_b32 s27, s15, s1
	s_cselect_b32 s26, s46, s0
	v_add_u32_e32 v140, s51, v143
	s_cselect_b32 s25, s13, s49
	s_cselect_b32 s24, s47, s48
	s_add_i32 s0, 0, 0x14000
	ds_read_b128 v[146:149], v140
	ds_read_b128 v[150:153], v140 offset:1024
	ds_read_b128 v[154:157], v140 offset:2048
	ds_read_b128 v[158:161], v140 offset:3072
	v_add_u32_e32 v140, s0, v143
	ds_read_b128 v[162:165], v140
	ds_read_b128 v[166:169], v140 offset:1024
	ds_read_b128 v[170:173], v140 offset:2048
	ds_read_b128 v[174:177], v140 offset:3072
	v_lshl_add_u64 v[140:141], s[22:23], 0, v[136:137]
	s_add_i32 m0, s35, 0xc000
	ds_read_b128 v[178:181], v144
	ds_read_b128 v[182:185], v144 offset:1024
	ds_read_b128 v[192:195], v144 offset:2048
	ds_read_b128 v[196:199], v144 offset:3072
	ds_read_b128 v[200:203], v144 offset:4096
	ds_read_b128 v[204:207], v144 offset:5120
	ds_read_b128 v[208:211], v144 offset:6144
	ds_read_b128 v[212:215], v144 offset:7168
	global_load_lds_dwordx4 v[140:141], off
	v_lshl_add_u64 v[140:141], s[22:23], 0, v[138:139]
	s_add_i32 m0, s35, 0xe000
	s_nop 0
	global_load_lds_dwordx4 v[140:141], off
	s_waitcnt vmcnt(8)
	s_waitcnt lgkmcnt(0)
	s_setprio 1
	s_barrier

	v_mfma_f32_16x16x32_bf16 v[126:129], v[146:149], v[178:181], v[126:129]
	v_mfma_f32_16x16x32_bf16 v[118:121], v[154:157], v[178:181], v[118:121]
	v_mfma_f32_16x16x32_bf16 v[110:113], v[146:149], v[192:195], v[110:113]
	v_mfma_f32_16x16x32_bf16 v[102:105], v[154:157], v[192:195], v[102:105]
	v_mfma_f32_16x16x32_bf16 v[94:97], v[146:149], v[200:203], v[94:97]
	v_mfma_f32_16x16x32_bf16 v[86:89], v[154:157], v[200:203], v[86:89]
	v_mfma_f32_16x16x32_bf16 v[78:81], v[146:149], v[208:211], v[78:81]
	v_mfma_f32_16x16x32_bf16 v[70:73], v[154:157], v[208:211], v[70:73]
	v_mfma_f32_16x16x32_bf16 v[126:129], v[150:153], v[182:185], v[126:129]
	v_mfma_f32_16x16x32_bf16 v[118:121], v[158:161], v[182:185], v[118:121]
	v_mfma_f32_16x16x32_bf16 v[110:113], v[150:153], v[196:199], v[110:113]
	v_mfma_f32_16x16x32_bf16 v[102:105], v[158:161], v[196:199], v[102:105]
	v_mfma_f32_16x16x32_bf16 v[94:97], v[150:153], v[204:207], v[94:97]
	v_mfma_f32_16x16x32_bf16 v[86:89], v[158:161], v[204:207], v[86:89]
	v_mfma_f32_16x16x32_bf16 v[78:81], v[150:153], v[212:215], v[78:81]
	v_mfma_f32_16x16x32_bf16 v[70:73], v[158:161], v[212:215], v[70:73]


	v_mfma_f32_16x16x32_bf16 v[122:125], v[162:165], v[178:181], v[122:125]
	v_mfma_f32_16x16x32_bf16 v[114:117], v[170:173], v[178:181], v[114:117]
	v_mfma_f32_16x16x32_bf16 v[106:109], v[162:165], v[192:195], v[106:109]
	v_mfma_f32_16x16x32_bf16 v[98:101], v[170:173], v[192:195], v[98:101]
	v_mfma_f32_16x16x32_bf16 v[90:93], v[162:165], v[200:203], v[90:93]
	v_mfma_f32_16x16x32_bf16 v[82:85], v[170:173], v[200:203], v[82:85]
	v_mfma_f32_16x16x32_bf16 v[74:77], v[162:165], v[208:211], v[74:77]
	v_mfma_f32_16x16x32_bf16 v[66:69], v[170:173], v[208:211], v[66:69]
	v_mfma_f32_16x16x32_bf16 v[122:125], v[166:169], v[182:185], v[122:125]
	v_mfma_f32_16x16x32_bf16 v[114:117], v[174:177], v[182:185], v[114:117]
	v_mfma_f32_16x16x32_bf16 v[106:109], v[166:169], v[196:199], v[106:109]
	v_mfma_f32_16x16x32_bf16 v[98:101], v[174:177], v[196:199], v[98:101]
	v_mfma_f32_16x16x32_bf16 v[90:93], v[166:169], v[204:207], v[90:93]
	v_mfma_f32_16x16x32_bf16 v[82:85], v[174:177], v[204:207], v[82:85]
	v_mfma_f32_16x16x32_bf16 v[74:77], v[166:169], v[212:215], v[74:77]
	v_mfma_f32_16x16x32_bf16 v[66:69], v[174:177], v[212:215], v[66:69]
	s_barrier
	s_setprio 0
	s_add_i32 s1, s51, s31
	v_lshl_add_u64 v[140:141], s[24:25], 0, v[186:187]
	s_mov_b32 m0, s1
	ds_read_b128 v[178:181], v144 offset:16384
	ds_read_b128 v[182:185], v144 offset:17408
	ds_read_b128 v[192:195], v144 offset:18432
	ds_read_b128 v[196:199], v144 offset:19456
	ds_read_b128 v[200:203], v144 offset:20480
	ds_read_b128 v[204:207], v144 offset:21504
	ds_read_b128 v[208:211], v144 offset:22528
	ds_read_b128 v[212:215], v144 offset:23552
	global_load_lds_dwordx4 v[140:141], off
	s_add_i32 m0, s1, 0x2000
	s_add_u32 s52, s24, 0x80000
	v_lshl_add_u64 v[216:217], s[24:25], 0, v[130:131]
	s_addc_u32 s53, s25, 0
	s_add_i32 s0, s0, s31
	global_load_lds_dwordx4 v[216:217], off
	v_lshl_add_u64 v[218:219], s[52:53], 0, v[186:187]
	s_mov_b32 m0, s0
	v_lshl_add_u64 v[220:221], s[26:27], 0, v[132:133]
	global_load_lds_dwordx4 v[218:219], off
	v_lshl_add_u64 v[218:219], s[52:53], 0, v[130:131]
	s_add_i32 m0, s0, 0x2000
	s_nop 0
	global_load_lds_dwordx4 v[218:219], off
	v_lshl_add_u64 v[218:219], s[26:27], 0, v[134:135]
	s_mov_b32 m0, s35
	s_nop 0
	global_load_lds_dwordx4 v[218:219], off
	s_mov_b32 m0, s36
	s_nop 0
	global_load_lds_dwordx4 v[220:221], off
	s_waitcnt vmcnt(8)
	s_waitcnt lgkmcnt(0)
	s_setprio 1
	s_barrier

	v_mfma_f32_16x16x32_bf16 v[62:65], v[146:149], v[178:181], v[62:65]
	v_mfma_f32_16x16x32_bf16 v[54:57], v[154:157], v[178:181], v[54:57]
	v_mfma_f32_16x16x32_bf16 v[46:49], v[146:149], v[192:195], v[46:49]
	v_mfma_f32_16x16x32_bf16 v[38:41], v[154:157], v[192:195], v[38:41]
	v_mfma_f32_16x16x32_bf16 v[30:33], v[146:149], v[200:203], v[30:33]
	v_mfma_f32_16x16x32_bf16 v[22:25], v[154:157], v[200:203], v[22:25]
	v_mfma_f32_16x16x32_bf16 v[14:17], v[146:149], v[208:211], v[14:17]
	v_mfma_f32_16x16x32_bf16 v[6:9], v[154:157], v[208:211], v[6:9]
	v_mfma_f32_16x16x32_bf16 v[62:65], v[150:153], v[182:185], v[62:65]
	v_mfma_f32_16x16x32_bf16 v[54:57], v[158:161], v[182:185], v[54:57]
	v_mfma_f32_16x16x32_bf16 v[46:49], v[150:153], v[196:199], v[46:49]
	v_mfma_f32_16x16x32_bf16 v[38:41], v[158:161], v[196:199], v[38:41]
	v_mfma_f32_16x16x32_bf16 v[30:33], v[150:153], v[204:207], v[30:33]
	v_mfma_f32_16x16x32_bf16 v[22:25], v[158:161], v[204:207], v[22:25]
	v_mfma_f32_16x16x32_bf16 v[14:17], v[150:153], v[212:215], v[14:17]
	v_mfma_f32_16x16x32_bf16 v[6:9], v[158:161], v[212:215], v[6:9]


	v_mfma_f32_16x16x32_bf16 v[58:61], v[162:165], v[178:181], v[58:61]
	v_mfma_f32_16x16x32_bf16 v[50:53], v[170:173], v[178:181], v[50:53]
	v_mfma_f32_16x16x32_bf16 v[42:45], v[162:165], v[192:195], v[42:45]
	v_mfma_f32_16x16x32_bf16 v[34:37], v[170:173], v[192:195], v[34:37]
	v_mfma_f32_16x16x32_bf16 v[26:29], v[162:165], v[200:203], v[26:29]
	v_mfma_f32_16x16x32_bf16 v[18:21], v[170:173], v[200:203], v[18:21]
	v_mfma_f32_16x16x32_bf16 v[10:13], v[162:165], v[208:211], v[10:13]
	v_mfma_f32_16x16x32_bf16 v[2:5], v[170:173], v[208:211], v[2:5]
	v_mfma_f32_16x16x32_bf16 v[58:61], v[166:169], v[182:185], v[58:61]
	v_mfma_f32_16x16x32_bf16 v[50:53], v[174:177], v[182:185], v[50:53]
	v_mfma_f32_16x16x32_bf16 v[42:45], v[166:169], v[196:199], v[42:45]
	v_mfma_f32_16x16x32_bf16 v[34:37], v[174:177], v[196:199], v[34:37]
	v_mfma_f32_16x16x32_bf16 v[26:29], v[166:169], v[204:207], v[26:29]
	v_mfma_f32_16x16x32_bf16 v[18:21], v[174:177], v[204:207], v[18:21]
	v_mfma_f32_16x16x32_bf16 v[10:13], v[166:169], v[212:215], v[10:13]
	v_mfma_f32_16x16x32_bf16 v[2:5], v[174:177], v[212:215], v[2:5]
	s_barrier
	s_setprio 0
	s_add_i32 s0, 0, 0x18000
	v_add_u32_e32 v145, s0, v143
	s_add_i32 s1, 0, 0x1c000
	ds_read_b128 v[146:149], v145
	ds_read_b128 v[150:153], v145 offset:1024
	ds_read_b128 v[154:157], v145 offset:2048
	ds_read_b128 v[158:161], v145 offset:3072
	v_add_u32_e32 v145, s1, v143
	ds_read_b128 v[162:165], v145
	ds_read_b128 v[166:169], v145 offset:1024
	ds_read_b128 v[170:173], v145 offset:2048
	ds_read_b128 v[174:177], v145 offset:3072
	s_add_u32 s26, s26, 0x80000
	s_addc_u32 s27, s27, 0
	s_mov_b32 m0, s37
	v_lshl_add_u64 v[222:223], s[26:27], 0, v[134:135]
	ds_read_b128 v[178:181], v144 offset:32768
	ds_read_b128 v[182:185], v144 offset:33792
	ds_read_b128 v[192:195], v144 offset:34816
	ds_read_b128 v[196:199], v144 offset:35840
	ds_read_b128 v[200:203], v144 offset:36864
	ds_read_b128 v[204:207], v144 offset:37888
	ds_read_b128 v[208:211], v144 offset:38912
	ds_read_b128 v[212:215], v144 offset:39936
	global_load_lds_dwordx4 v[222:223], off
	v_lshl_add_u64 v[222:223], s[26:27], 0, v[132:133]
	s_mov_b32 m0, s38
	s_nop 0
	global_load_lds_dwordx4 v[222:223], off
	s_waitcnt vmcnt(8)
	s_waitcnt lgkmcnt(0)
	s_setprio 1
	s_barrier

	v_mfma_f32_16x16x32_bf16 v[126:129], v[146:149], v[178:181], v[126:129]
	v_mfma_f32_16x16x32_bf16 v[118:121], v[154:157], v[178:181], v[118:121]
	v_mfma_f32_16x16x32_bf16 v[110:113], v[146:149], v[192:195], v[110:113]
	v_mfma_f32_16x16x32_bf16 v[102:105], v[154:157], v[192:195], v[102:105]
	v_mfma_f32_16x16x32_bf16 v[94:97], v[146:149], v[200:203], v[94:97]
	v_mfma_f32_16x16x32_bf16 v[86:89], v[154:157], v[200:203], v[86:89]
	v_mfma_f32_16x16x32_bf16 v[78:81], v[146:149], v[208:211], v[78:81]
	v_mfma_f32_16x16x32_bf16 v[70:73], v[154:157], v[208:211], v[70:73]
	v_mfma_f32_16x16x32_bf16 v[126:129], v[150:153], v[182:185], v[126:129]
	v_mfma_f32_16x16x32_bf16 v[118:121], v[158:161], v[182:185], v[118:121]
	v_mfma_f32_16x16x32_bf16 v[110:113], v[150:153], v[196:199], v[110:113]
	v_mfma_f32_16x16x32_bf16 v[102:105], v[158:161], v[196:199], v[102:105]
	v_mfma_f32_16x16x32_bf16 v[94:97], v[150:153], v[204:207], v[94:97]
	v_mfma_f32_16x16x32_bf16 v[86:89], v[158:161], v[204:207], v[86:89]
	v_mfma_f32_16x16x32_bf16 v[78:81], v[150:153], v[212:215], v[78:81]
	v_mfma_f32_16x16x32_bf16 v[70:73], v[158:161], v[212:215], v[70:73]


	v_mfma_f32_16x16x32_bf16 v[122:125], v[162:165], v[178:181], v[122:125]
	v_mfma_f32_16x16x32_bf16 v[114:117], v[170:173], v[178:181], v[114:117]
	v_mfma_f32_16x16x32_bf16 v[106:109], v[162:165], v[192:195], v[106:109]
	v_mfma_f32_16x16x32_bf16 v[98:101], v[170:173], v[192:195], v[98:101]
	v_mfma_f32_16x16x32_bf16 v[90:93], v[162:165], v[200:203], v[90:93]
	v_mfma_f32_16x16x32_bf16 v[82:85], v[170:173], v[200:203], v[82:85]
	v_mfma_f32_16x16x32_bf16 v[74:77], v[162:165], v[208:211], v[74:77]
	v_mfma_f32_16x16x32_bf16 v[66:69], v[170:173], v[208:211], v[66:69]
	v_mfma_f32_16x16x32_bf16 v[122:125], v[166:169], v[182:185], v[122:125]
	v_mfma_f32_16x16x32_bf16 v[114:117], v[174:177], v[182:185], v[114:117]
	v_mfma_f32_16x16x32_bf16 v[106:109], v[166:169], v[196:199], v[106:109]
	v_mfma_f32_16x16x32_bf16 v[98:101], v[174:177], v[196:199], v[98:101]
	v_mfma_f32_16x16x32_bf16 v[90:93], v[166:169], v[204:207], v[90:93]
	v_mfma_f32_16x16x32_bf16 v[82:85], v[174:177], v[204:207], v[82:85]
	v_mfma_f32_16x16x32_bf16 v[74:77], v[166:169], v[212:215], v[74:77]
	v_mfma_f32_16x16x32_bf16 v[66:69], v[174:177], v[212:215], v[66:69]
	s_barrier
	s_setprio 0
	s_add_i32 s0, s0, s31
	v_lshl_add_u64 v[140:141], v[140:141], 0, s[84:85]
	s_mov_b32 m0, s0
	ds_read_b128 v[178:181], v144 offset:49152
	ds_read_b128 v[182:185], v144 offset:50176
	ds_read_b128 v[192:195], v144 offset:51200
	ds_read_b128 v[196:199], v144 offset:52224
	ds_read_b128 v[200:203], v144 offset:53248
	ds_read_b128 v[204:207], v144 offset:54272
	ds_read_b128 v[208:211], v144 offset:55296
	ds_read_b128 v[212:215], v144 offset:56320
	global_load_lds_dwordx4 v[140:141], off
	s_add_i32 m0, s0, 0x2000
	s_add_u32 s24, s24, 0x80080
	v_lshl_add_u64 v[140:141], v[216:217], 0, s[84:85]
	s_addc_u32 s25, s25, 0
	s_add_i32 s0, s1, s31
	global_load_lds_dwordx4 v[140:141], off
	v_lshl_add_u64 v[140:141], s[24:25], 0, v[186:187]
	s_mov_b32 m0, s0
	s_nop 0
	global_load_lds_dwordx4 v[140:141], off
	v_lshl_add_u64 v[140:141], s[24:25], 0, v[130:131]
	s_add_i32 m0, s0, 0x2000
	s_nop 0
	global_load_lds_dwordx4 v[140:141], off
	v_lshl_add_u64 v[140:141], v[218:219], 0, s[84:85]
	s_mov_b32 m0, s39
	s_nop 0
	global_load_lds_dwordx4 v[140:141], off
	v_lshl_add_u64 v[140:141], v[220:221], 0, s[84:85]
	s_mov_b32 m0, s40
	s_nop 0
	global_load_lds_dwordx4 v[140:141], off
	s_waitcnt vmcnt(8)
	s_waitcnt lgkmcnt(0)
	s_setprio 1
	s_barrier

	v_mfma_f32_16x16x32_bf16 v[62:65], v[146:149], v[178:181], v[62:65]
	v_mfma_f32_16x16x32_bf16 v[54:57], v[154:157], v[178:181], v[54:57]
	v_mfma_f32_16x16x32_bf16 v[46:49], v[146:149], v[192:195], v[46:49]
	v_mfma_f32_16x16x32_bf16 v[38:41], v[154:157], v[192:195], v[38:41]
	v_mfma_f32_16x16x32_bf16 v[30:33], v[146:149], v[200:203], v[30:33]
	v_mfma_f32_16x16x32_bf16 v[22:25], v[154:157], v[200:203], v[22:25]
	v_mfma_f32_16x16x32_bf16 v[14:17], v[146:149], v[208:211], v[14:17]
	v_mfma_f32_16x16x32_bf16 v[6:9], v[154:157], v[208:211], v[6:9]
	v_mfma_f32_16x16x32_bf16 v[62:65], v[150:153], v[182:185], v[62:65]
	v_mfma_f32_16x16x32_bf16 v[54:57], v[158:161], v[182:185], v[54:57]
	v_mfma_f32_16x16x32_bf16 v[46:49], v[150:153], v[196:199], v[46:49]
	v_mfma_f32_16x16x32_bf16 v[38:41], v[158:161], v[196:199], v[38:41]
	v_mfma_f32_16x16x32_bf16 v[30:33], v[150:153], v[204:207], v[30:33]
	v_mfma_f32_16x16x32_bf16 v[22:25], v[158:161], v[204:207], v[22:25]
	v_mfma_f32_16x16x32_bf16 v[14:17], v[150:153], v[212:215], v[14:17]
	v_mfma_f32_16x16x32_bf16 v[6:9], v[158:161], v[212:215], v[6:9]


	v_mfma_f32_16x16x32_bf16 v[58:61], v[162:165], v[178:181], v[58:61]
	v_mfma_f32_16x16x32_bf16 v[50:53], v[170:173], v[178:181], v[50:53]
	v_mfma_f32_16x16x32_bf16 v[42:45], v[162:165], v[192:195], v[42:45]
	v_mfma_f32_16x16x32_bf16 v[34:37], v[170:173], v[192:195], v[34:37]
	v_mfma_f32_16x16x32_bf16 v[26:29], v[162:165], v[200:203], v[26:29]
	v_mfma_f32_16x16x32_bf16 v[18:21], v[170:173], v[200:203], v[18:21]
	v_mfma_f32_16x16x32_bf16 v[10:13], v[162:165], v[208:211], v[10:13]
	v_mfma_f32_16x16x32_bf16 v[2:5], v[170:173], v[208:211], v[2:5]
	v_mfma_f32_16x16x32_bf16 v[58:61], v[166:169], v[182:185], v[58:61]
	v_mfma_f32_16x16x32_bf16 v[50:53], v[174:177], v[182:185], v[50:53]
	v_mfma_f32_16x16x32_bf16 v[42:45], v[166:169], v[196:199], v[42:45]
	v_mfma_f32_16x16x32_bf16 v[34:37], v[174:177], v[196:199], v[34:37]
	v_mfma_f32_16x16x32_bf16 v[26:29], v[166:169], v[204:207], v[26:29]
	v_mfma_f32_16x16x32_bf16 v[18:21], v[174:177], v[204:207], v[18:21]
	v_mfma_f32_16x16x32_bf16 v[10:13], v[166:169], v[212:215], v[10:13]
	v_mfma_f32_16x16x32_bf16 v[2:5], v[174:177], v[212:215], v[2:5]
	s_barrier
	s_setprio 0
	s_add_i32 s50, s50, 2
	s_add_u32 s22, s22, 0x100
	s_addc_u32 s23, s23, 0
	s_add_u32 s48, s48, 0x100
	s_addc_u32 s49, s49, 0
	s_cmp_gt_u32 s50, 29
	s_cbranch_scc0 .LBB0_159
	s_and_b64 vcc, exec, s[10:11]
	s_cbranch_vccz .LBB0_162
	s_barrier

.LBB0_243:
	s_add_u32 s22, s20, 0x100
	s_addc_u32 s23, s21, 0
	s_add_i32 s0, 0, 0x10000
	s_cmpk_eq_i32 s51, 0x54
	s_cselect_b32 s27, s7, s23
	s_cselect_b32 s26, s6, s22
	s_cselect_b32 s25, s19, s50
	s_cselect_b32 s24, s18, s49
	s_add_i32 s1, 0, 0x14000
	v_add_u32_e32 v126, s0, v237
	v_add_u32_e32 v158, s1, v237
	ds_read_b128 v[90:93], v126
	ds_read_b128 v[102:105], v126 offset:1024
	ds_read_b128 v[114:117], v126 offset:2048
	ds_read_b128 v[126:129], v126 offset:3072
	ds_read_b128 v[138:141], v158
	ds_read_b128 v[142:145], v158 offset:1024
	ds_read_b128 v[154:157], v158 offset:2048
	ds_read_b128 v[158:161], v158 offset:3072
	v_lshl_add_u64 v[210:211], s[20:21], 0, v[198:199]
	s_add_i32 m0, s34, 0xc000
	ds_read_b128 v[162:165], v238
	ds_read_b128 v[166:169], v238 offset:1024
	ds_read_b128 v[170:173], v238 offset:2048
	ds_read_b128 v[174:177], v238 offset:3072
	ds_read_b128 v[178:181], v238 offset:4096
	ds_read_b128 v[182:185], v238 offset:5120
	ds_read_b128 v[202:205], v238 offset:6144
	ds_read_b128 v[206:209], v238 offset:7168
	global_load_lds_dwordx4 v[210:211], off
	v_lshl_add_u64 v[210:211], s[20:21], 0, v[200:201]
	s_add_i32 m0, s34, 0xe000
	s_nop 0
	global_load_lds_dwordx4 v[210:211], off
	s_waitcnt vmcnt(8)
	s_waitcnt lgkmcnt(0)
	s_setprio 1
	s_barrier

	v_mfma_f32_16x16x32_bf16 v[150:153], v[90:93], v[162:165], v[150:153]
	v_mfma_f32_16x16x32_bf16 v[146:149], v[114:117], v[162:165], v[146:149]
	v_mfma_f32_16x16x32_bf16 v[122:125], v[90:93], v[170:173], v[122:125]
	v_mfma_f32_16x16x32_bf16 v[118:121], v[114:117], v[170:173], v[118:121]
	v_mfma_f32_16x16x32_bf16 v[98:101], v[90:93], v[178:181], v[98:101]
	v_mfma_f32_16x16x32_bf16 v[94:97], v[114:117], v[178:181], v[94:97]
	v_mfma_f32_16x16x32_bf16 v[78:81], v[90:93], v[202:205], v[78:81]
	v_mfma_f32_16x16x32_bf16 v[74:77], v[114:117], v[202:205], v[74:77]
	v_mfma_f32_16x16x32_bf16 v[150:153], v[102:105], v[166:169], v[150:153]
	v_mfma_f32_16x16x32_bf16 v[146:149], v[126:129], v[166:169], v[146:149]
	v_mfma_f32_16x16x32_bf16 v[122:125], v[102:105], v[174:177], v[122:125]
	v_mfma_f32_16x16x32_bf16 v[118:121], v[126:129], v[174:177], v[118:121]
	v_mfma_f32_16x16x32_bf16 v[98:101], v[102:105], v[182:185], v[98:101]
	v_mfma_f32_16x16x32_bf16 v[94:97], v[126:129], v[182:185], v[94:97]
	v_mfma_f32_16x16x32_bf16 v[78:81], v[102:105], v[206:209], v[78:81]
	v_mfma_f32_16x16x32_bf16 v[74:77], v[126:129], v[206:209], v[74:77]


	v_mfma_f32_16x16x32_bf16 v[134:137], v[138:141], v[162:165], v[134:137]
	v_mfma_f32_16x16x32_bf16 v[130:133], v[154:157], v[162:165], v[130:133]
	v_mfma_f32_16x16x32_bf16 v[110:113], v[138:141], v[170:173], v[110:113]
	v_mfma_f32_16x16x32_bf16 v[106:109], v[154:157], v[170:173], v[106:109]
	v_mfma_f32_16x16x32_bf16 v[86:89], v[138:141], v[178:181], v[86:89]
	v_mfma_f32_16x16x32_bf16 v[82:85], v[154:157], v[178:181], v[82:85]
	v_mfma_f32_16x16x32_bf16 v[70:73], v[138:141], v[202:205], v[70:73]
	v_mfma_f32_16x16x32_bf16 v[66:69], v[154:157], v[202:205], v[66:69]
	v_mfma_f32_16x16x32_bf16 v[134:137], v[142:145], v[166:169], v[134:137]
	v_mfma_f32_16x16x32_bf16 v[130:133], v[158:161], v[166:169], v[130:133]
	v_mfma_f32_16x16x32_bf16 v[110:113], v[142:145], v[174:177], v[110:113]
	v_mfma_f32_16x16x32_bf16 v[106:109], v[158:161], v[174:177], v[106:109]
	v_mfma_f32_16x16x32_bf16 v[86:89], v[142:145], v[182:185], v[86:89]
	v_mfma_f32_16x16x32_bf16 v[82:85], v[158:161], v[182:185], v[82:85]
	v_mfma_f32_16x16x32_bf16 v[70:73], v[142:145], v[206:209], v[70:73]
	v_mfma_f32_16x16x32_bf16 v[66:69], v[158:161], v[206:209], v[66:69]
	s_barrier
	s_setprio 0
	s_add_i32 s0, s0, s31
	v_lshl_add_u64 v[210:211], s[24:25], 0, v[186:187]
	s_mov_b32 m0, s0
	ds_read_b128 v[162:165], v238 offset:16384
	ds_read_b128 v[166:169], v238 offset:17408
	ds_read_b128 v[170:173], v238 offset:18432
	ds_read_b128 v[174:177], v238 offset:19456
	ds_read_b128 v[178:181], v238 offset:20480
	ds_read_b128 v[182:185], v238 offset:21504
	ds_read_b128 v[202:205], v238 offset:22528
	ds_read_b128 v[206:209], v238 offset:23552
	global_load_lds_dwordx4 v[210:211], off
	s_add_i32 m0, s0, 0x2000
	s_add_u32 s20, s24, 0x160000
	v_lshl_add_u64 v[212:213], s[24:25], 0, v[196:197]
	s_addc_u32 s21, s25, 0
	s_add_i32 s0, s1, s31
	global_load_lds_dwordx4 v[212:213], off
	v_lshl_add_u64 v[214:215], s[20:21], 0, v[186:187]
	s_mov_b32 m0, s0
	v_lshl_add_u64 v[216:217], s[26:27], 0, v[194:195]
	global_load_lds_dwordx4 v[214:215], off
	v_lshl_add_u64 v[214:215], s[20:21], 0, v[196:197]
	s_add_i32 m0, s0, 0x2000
	s_nop 0
	global_load_lds_dwordx4 v[214:215], off
	v_lshl_add_u64 v[214:215], s[26:27], 0, v[192:193]
	s_mov_b32 m0, s34
	s_nop 0
	global_load_lds_dwordx4 v[214:215], off
	s_mov_b32 m0, s35
	s_nop 0
	global_load_lds_dwordx4 v[216:217], off
	s_waitcnt vmcnt(8)
	s_waitcnt lgkmcnt(0)
	s_setprio 1
	s_barrier

	v_mfma_f32_16x16x32_bf16 v[62:65], v[90:93], v[162:165], v[62:65]
	v_mfma_f32_16x16x32_bf16 v[58:61], v[114:117], v[162:165], v[58:61]
	v_mfma_f32_16x16x32_bf16 v[46:49], v[90:93], v[170:173], v[46:49]
	v_mfma_f32_16x16x32_bf16 v[42:45], v[114:117], v[170:173], v[42:45]
	v_mfma_f32_16x16x32_bf16 v[30:33], v[90:93], v[178:181], v[30:33]
	v_mfma_f32_16x16x32_bf16 v[26:29], v[114:117], v[178:181], v[26:29]
	v_mfma_f32_16x16x32_bf16 v[14:17], v[90:93], v[202:205], v[14:17]
	v_mfma_f32_16x16x32_bf16 v[10:13], v[114:117], v[202:205], v[10:13]
	v_mfma_f32_16x16x32_bf16 v[62:65], v[102:105], v[166:169], v[62:65]
	v_mfma_f32_16x16x32_bf16 v[58:61], v[126:129], v[166:169], v[58:61]
	v_mfma_f32_16x16x32_bf16 v[46:49], v[102:105], v[174:177], v[46:49]
	v_mfma_f32_16x16x32_bf16 v[42:45], v[126:129], v[174:177], v[42:45]
	v_mfma_f32_16x16x32_bf16 v[30:33], v[102:105], v[182:185], v[30:33]
	v_mfma_f32_16x16x32_bf16 v[26:29], v[126:129], v[182:185], v[26:29]
	v_mfma_f32_16x16x32_bf16 v[14:17], v[102:105], v[206:209], v[14:17]
	v_mfma_f32_16x16x32_bf16 v[10:13], v[126:129], v[206:209], v[10:13]


	v_mfma_f32_16x16x32_bf16 v[54:57], v[138:141], v[162:165], v[54:57]
	v_mfma_f32_16x16x32_bf16 v[50:53], v[154:157], v[162:165], v[50:53]
	v_mfma_f32_16x16x32_bf16 v[38:41], v[138:141], v[170:173], v[38:41]
	v_mfma_f32_16x16x32_bf16 v[34:37], v[154:157], v[170:173], v[34:37]
	v_mfma_f32_16x16x32_bf16 v[22:25], v[138:141], v[178:181], v[22:25]
	v_mfma_f32_16x16x32_bf16 v[18:21], v[154:157], v[178:181], v[18:21]
	v_mfma_f32_16x16x32_bf16 v[6:9], v[138:141], v[202:205], v[6:9]
	v_mfma_f32_16x16x32_bf16 v[2:5], v[154:157], v[202:205], v[2:5]
	v_mfma_f32_16x16x32_bf16 v[54:57], v[142:145], v[166:169], v[54:57]
	v_mfma_f32_16x16x32_bf16 v[50:53], v[158:161], v[166:169], v[50:53]
	v_mfma_f32_16x16x32_bf16 v[38:41], v[142:145], v[174:177], v[38:41]
	v_mfma_f32_16x16x32_bf16 v[34:37], v[158:161], v[174:177], v[34:37]
	v_mfma_f32_16x16x32_bf16 v[22:25], v[142:145], v[182:185], v[22:25]
	v_mfma_f32_16x16x32_bf16 v[18:21], v[158:161], v[182:185], v[18:21]
	v_mfma_f32_16x16x32_bf16 v[6:9], v[142:145], v[206:209], v[6:9]
	v_mfma_f32_16x16x32_bf16 v[2:5], v[158:161], v[206:209], v[2:5]
	s_barrier
	s_setprio 0
	s_add_i32 s0, 0, 0x18000
	s_add_i32 s1, 0, 0x1c000
	v_add_u32_e32 v126, s0, v237
	v_add_u32_e32 v158, s1, v237
	ds_read_b128 v[90:93], v126
	ds_read_b128 v[102:105], v126 offset:1024
	ds_read_b128 v[114:117], v126 offset:2048
	ds_read_b128 v[126:129], v126 offset:3072
	ds_read_b128 v[138:141], v158
	ds_read_b128 v[142:145], v158 offset:1024
	ds_read_b128 v[154:157], v158 offset:2048
	ds_read_b128 v[158:161], v158 offset:3072
	s_add_u32 s20, s26, 0x160000
	s_addc_u32 s21, s27, 0
	s_mov_b32 m0, s36
	v_lshl_add_u64 v[218:219], s[20:21], 0, v[192:193]
	ds_read_b128 v[162:165], v238 offset:32768
	ds_read_b128 v[166:169], v238 offset:33792
	ds_read_b128 v[170:173], v238 offset:34816
	ds_read_b128 v[174:177], v238 offset:35840
	ds_read_b128 v[178:181], v238 offset:36864
	ds_read_b128 v[182:185], v238 offset:37888
	ds_read_b128 v[202:205], v238 offset:38912
	ds_read_b128 v[206:209], v238 offset:39936
	global_load_lds_dwordx4 v[218:219], off
	v_lshl_add_u64 v[218:219], s[20:21], 0, v[194:195]
	s_mov_b32 m0, s37
	s_nop 0
	global_load_lds_dwordx4 v[218:219], off
	s_waitcnt vmcnt(8)
	s_waitcnt lgkmcnt(0)
	s_setprio 1
	s_barrier

	v_mfma_f32_16x16x32_bf16 v[150:153], v[90:93], v[162:165], v[150:153]
	v_mfma_f32_16x16x32_bf16 v[146:149], v[114:117], v[162:165], v[146:149]
	v_mfma_f32_16x16x32_bf16 v[122:125], v[90:93], v[170:173], v[122:125]
	v_mfma_f32_16x16x32_bf16 v[118:121], v[114:117], v[170:173], v[118:121]
	v_mfma_f32_16x16x32_bf16 v[98:101], v[90:93], v[178:181], v[98:101]
	v_mfma_f32_16x16x32_bf16 v[94:97], v[114:117], v[178:181], v[94:97]
	v_mfma_f32_16x16x32_bf16 v[78:81], v[90:93], v[202:205], v[78:81]
	v_mfma_f32_16x16x32_bf16 v[74:77], v[114:117], v[202:205], v[74:77]
	v_mfma_f32_16x16x32_bf16 v[150:153], v[102:105], v[166:169], v[150:153]
	v_mfma_f32_16x16x32_bf16 v[146:149], v[126:129], v[166:169], v[146:149]
	v_mfma_f32_16x16x32_bf16 v[122:125], v[102:105], v[174:177], v[122:125]
	v_mfma_f32_16x16x32_bf16 v[118:121], v[126:129], v[174:177], v[118:121]
	v_mfma_f32_16x16x32_bf16 v[98:101], v[102:105], v[182:185], v[98:101]
	v_mfma_f32_16x16x32_bf16 v[94:97], v[126:129], v[182:185], v[94:97]
	v_mfma_f32_16x16x32_bf16 v[78:81], v[102:105], v[206:209], v[78:81]
	v_mfma_f32_16x16x32_bf16 v[74:77], v[126:129], v[206:209], v[74:77]


	v_mfma_f32_16x16x32_bf16 v[134:137], v[138:141], v[162:165], v[134:137]
	v_mfma_f32_16x16x32_bf16 v[130:133], v[154:157], v[162:165], v[130:133]
	v_mfma_f32_16x16x32_bf16 v[110:113], v[138:141], v[170:173], v[110:113]
	v_mfma_f32_16x16x32_bf16 v[106:109], v[154:157], v[170:173], v[106:109]
	v_mfma_f32_16x16x32_bf16 v[86:89], v[138:141], v[178:181], v[86:89]
	v_mfma_f32_16x16x32_bf16 v[82:85], v[154:157], v[178:181], v[82:85]
	v_mfma_f32_16x16x32_bf16 v[70:73], v[138:141], v[202:205], v[70:73]
	v_mfma_f32_16x16x32_bf16 v[66:69], v[154:157], v[202:205], v[66:69]
	v_mfma_f32_16x16x32_bf16 v[134:137], v[142:145], v[166:169], v[134:137]
	v_mfma_f32_16x16x32_bf16 v[130:133], v[158:161], v[166:169], v[130:133]
	v_mfma_f32_16x16x32_bf16 v[110:113], v[142:145], v[174:177], v[110:113]
	v_mfma_f32_16x16x32_bf16 v[106:109], v[158:161], v[174:177], v[106:109]
	v_mfma_f32_16x16x32_bf16 v[86:89], v[142:145], v[182:185], v[86:89]
	v_mfma_f32_16x16x32_bf16 v[82:85], v[158:161], v[182:185], v[82:85]
	v_mfma_f32_16x16x32_bf16 v[70:73], v[142:145], v[206:209], v[70:73]
	v_mfma_f32_16x16x32_bf16 v[66:69], v[158:161], v[206:209], v[66:69]
	s_barrier
	s_setprio 0
	s_add_i32 s0, s0, s31
	v_lshl_add_u64 v[210:211], v[210:211], 0, s[84:85]
	s_mov_b32 m0, s0
	ds_read_b128 v[162:165], v238 offset:49152
	ds_read_b128 v[166:169], v238 offset:50176
	ds_read_b128 v[170:173], v238 offset:51200
	ds_read_b128 v[174:177], v238 offset:52224
	ds_read_b128 v[178:181], v238 offset:53248
	ds_read_b128 v[182:185], v238 offset:54272
	ds_read_b128 v[202:205], v238 offset:55296
	ds_read_b128 v[206:209], v238 offset:56320
	global_load_lds_dwordx4 v[210:211], off
	s_add_i32 m0, s0, 0x2000
	s_add_u32 s20, s24, 0x160080
	v_lshl_add_u64 v[210:211], v[212:213], 0, s[84:85]
	s_addc_u32 s21, s25, 0
	s_add_i32 s0, s1, s31
	global_load_lds_dwordx4 v[210:211], off
	v_lshl_add_u64 v[210:211], s[20:21], 0, v[186:187]
	s_mov_b32 m0, s0
	s_nop 0
	global_load_lds_dwordx4 v[210:211], off
	v_lshl_add_u64 v[210:211], s[20:21], 0, v[196:197]
	s_add_i32 m0, s0, 0x2000
	s_nop 0
	global_load_lds_dwordx4 v[210:211], off
	v_lshl_add_u64 v[210:211], v[214:215], 0, s[84:85]
	s_mov_b32 m0, s41
	s_nop 0
	global_load_lds_dwordx4 v[210:211], off
	v_lshl_add_u64 v[210:211], v[216:217], 0, s[84:85]
	s_mov_b32 m0, s42
	s_nop 0
	global_load_lds_dwordx4 v[210:211], off
	s_waitcnt vmcnt(8)
	s_waitcnt lgkmcnt(0)
	s_setprio 1
	s_barrier

	v_mfma_f32_16x16x32_bf16 v[62:65], v[90:93], v[162:165], v[62:65]
	v_mfma_f32_16x16x32_bf16 v[58:61], v[114:117], v[162:165], v[58:61]
	v_mfma_f32_16x16x32_bf16 v[46:49], v[90:93], v[170:173], v[46:49]
	v_mfma_f32_16x16x32_bf16 v[42:45], v[114:117], v[170:173], v[42:45]
	v_mfma_f32_16x16x32_bf16 v[30:33], v[90:93], v[178:181], v[30:33]
	v_mfma_f32_16x16x32_bf16 v[26:29], v[114:117], v[178:181], v[26:29]
	v_mfma_f32_16x16x32_bf16 v[14:17], v[90:93], v[202:205], v[14:17]
	v_mfma_f32_16x16x32_bf16 v[10:13], v[114:117], v[202:205], v[10:13]
	v_mfma_f32_16x16x32_bf16 v[62:65], v[102:105], v[166:169], v[62:65]
	v_mfma_f32_16x16x32_bf16 v[58:61], v[126:129], v[166:169], v[58:61]
	v_mfma_f32_16x16x32_bf16 v[46:49], v[102:105], v[174:177], v[46:49]
	v_mfma_f32_16x16x32_bf16 v[42:45], v[126:129], v[174:177], v[42:45]
	v_mfma_f32_16x16x32_bf16 v[30:33], v[102:105], v[182:185], v[30:33]
	v_mfma_f32_16x16x32_bf16 v[26:29], v[126:129], v[182:185], v[26:29]
	v_mfma_f32_16x16x32_bf16 v[14:17], v[102:105], v[206:209], v[14:17]
	v_mfma_f32_16x16x32_bf16 v[10:13], v[126:129], v[206:209], v[10:13]


	v_mfma_f32_16x16x32_bf16 v[54:57], v[138:141], v[162:165], v[54:57]
	v_mfma_f32_16x16x32_bf16 v[50:53], v[154:157], v[162:165], v[50:53]
	v_mfma_f32_16x16x32_bf16 v[38:41], v[138:141], v[170:173], v[38:41]
	v_mfma_f32_16x16x32_bf16 v[34:37], v[154:157], v[170:173], v[34:37]
	v_mfma_f32_16x16x32_bf16 v[22:25], v[138:141], v[178:181], v[22:25]
	v_mfma_f32_16x16x32_bf16 v[18:21], v[154:157], v[178:181], v[18:21]
	v_mfma_f32_16x16x32_bf16 v[6:9], v[138:141], v[202:205], v[6:9]
	v_mfma_f32_16x16x32_bf16 v[2:5], v[154:157], v[202:205], v[2:5]
	v_mfma_f32_16x16x32_bf16 v[54:57], v[142:145], v[166:169], v[54:57]
	v_mfma_f32_16x16x32_bf16 v[50:53], v[158:161], v[166:169], v[50:53]
	v_mfma_f32_16x16x32_bf16 v[38:41], v[142:145], v[174:177], v[38:41]
	v_mfma_f32_16x16x32_bf16 v[34:37], v[158:161], v[174:177], v[34:37]
	v_mfma_f32_16x16x32_bf16 v[22:25], v[142:145], v[182:185], v[22:25]
	v_mfma_f32_16x16x32_bf16 v[18:21], v[158:161], v[182:185], v[18:21]
	v_mfma_f32_16x16x32_bf16 v[6:9], v[142:145], v[206:209], v[6:9]
	v_mfma_f32_16x16x32_bf16 v[2:5], v[158:161], v[206:209], v[2:5]
	s_barrier
	s_setprio 0
	s_add_i32 s51, s51, 2
	s_add_u32 s49, s49, 0x100
	s_addc_u32 s50, s50, 0
	s_cmpk_gt_u32 s51, 0x55
	s_mov_b64 s[20:21], s[22:23]
	s_cbranch_scc0 .LBB0_243
	s_and_b64 vcc, exec, s[16:17]
	s_cbranch_vccz .LBB0_246
	s_barrier

.LBB0_443:
	s_add_u32 s0, s26, 0xfff80080
	s_addc_u32 s1, s27, -1
	s_add_i32 s56, 0, 0x10000
	s_cmp_eq_u32 s55, 28
	s_cselect_b32 s31, s19, s1
	s_cselect_b32 s30, s51, s0
	v_add_u32_e32 v140, s56, v144
	s_cselect_b32 s29, s17, s54
	s_cselect_b32 s28, s52, s53
	s_add_i32 s0, 0, 0x14000
	ds_read_b128 v[146:149], v140
	ds_read_b128 v[150:153], v140 offset:1024
	ds_read_b128 v[154:157], v140 offset:2048
	ds_read_b128 v[158:161], v140 offset:3072
	v_add_u32_e32 v140, s0, v144
	ds_read_b128 v[162:165], v140
	ds_read_b128 v[166:169], v140 offset:1024
	ds_read_b128 v[170:173], v140 offset:2048
	ds_read_b128 v[174:177], v140 offset:3072
	v_lshl_add_u64 v[140:141], s[26:27], 0, v[136:137]
	s_add_i32 m0, s25, 0xc000
	ds_read_b128 v[178:181], v145
	ds_read_b128 v[182:185], v145 offset:1024
	ds_read_b128 v[192:195], v145 offset:2048
	ds_read_b128 v[196:199], v145 offset:3072
	ds_read_b128 v[200:203], v145 offset:4096
	ds_read_b128 v[204:207], v145 offset:5120
	ds_read_b128 v[208:211], v145 offset:6144
	ds_read_b128 v[212:215], v145 offset:7168
	global_load_lds_dwordx4 v[140:141], off
	v_lshl_add_u64 v[140:141], s[26:27], 0, v[138:139]
	s_add_i32 m0, s25, 0xe000
	s_nop 0
	global_load_lds_dwordx4 v[140:141], off
	s_waitcnt vmcnt(8)
	s_waitcnt lgkmcnt(0)
	s_setprio 1
	s_barrier

	v_mfma_f32_16x16x32_bf16 v[126:129], v[146:149], v[178:181], v[126:129]
	v_mfma_f32_16x16x32_bf16 v[122:125], v[154:157], v[178:181], v[122:125]
	v_mfma_f32_16x16x32_bf16 v[114:117], v[146:149], v[192:195], v[114:117]
	v_mfma_f32_16x16x32_bf16 v[106:109], v[154:157], v[192:195], v[106:109]
	v_mfma_f32_16x16x32_bf16 v[98:101], v[146:149], v[200:203], v[98:101]
	v_mfma_f32_16x16x32_bf16 v[90:93], v[154:157], v[200:203], v[90:93]
	v_mfma_f32_16x16x32_bf16 v[82:85], v[146:149], v[208:211], v[82:85]
	v_mfma_f32_16x16x32_bf16 v[74:77], v[154:157], v[208:211], v[74:77]
	v_mfma_f32_16x16x32_bf16 v[126:129], v[150:153], v[182:185], v[126:129]
	v_mfma_f32_16x16x32_bf16 v[122:125], v[158:161], v[182:185], v[122:125]
	v_mfma_f32_16x16x32_bf16 v[114:117], v[150:153], v[196:199], v[114:117]
	v_mfma_f32_16x16x32_bf16 v[106:109], v[158:161], v[196:199], v[106:109]
	v_mfma_f32_16x16x32_bf16 v[98:101], v[150:153], v[204:207], v[98:101]
	v_mfma_f32_16x16x32_bf16 v[90:93], v[158:161], v[204:207], v[90:93]
	v_mfma_f32_16x16x32_bf16 v[82:85], v[150:153], v[212:215], v[82:85]
	v_mfma_f32_16x16x32_bf16 v[74:77], v[158:161], v[212:215], v[74:77]


	v_mfma_f32_16x16x32_bf16 v[118:121], v[162:165], v[178:181], v[118:121]
	v_mfma_f32_16x16x32_bf16 v[110:113], v[170:173], v[178:181], v[110:113]
	v_mfma_f32_16x16x32_bf16 v[102:105], v[162:165], v[192:195], v[102:105]
	v_mfma_f32_16x16x32_bf16 v[94:97], v[170:173], v[192:195], v[94:97]
	v_mfma_f32_16x16x32_bf16 v[86:89], v[162:165], v[200:203], v[86:89]
	v_mfma_f32_16x16x32_bf16 v[78:81], v[170:173], v[200:203], v[78:81]
	v_mfma_f32_16x16x32_bf16 v[70:73], v[162:165], v[208:211], v[70:73]
	v_mfma_f32_16x16x32_bf16 v[66:69], v[170:173], v[208:211], v[66:69]
	v_mfma_f32_16x16x32_bf16 v[118:121], v[166:169], v[182:185], v[118:121]
	v_mfma_f32_16x16x32_bf16 v[110:113], v[174:177], v[182:185], v[110:113]
	v_mfma_f32_16x16x32_bf16 v[102:105], v[166:169], v[196:199], v[102:105]
	v_mfma_f32_16x16x32_bf16 v[94:97], v[174:177], v[196:199], v[94:97]
	v_mfma_f32_16x16x32_bf16 v[86:89], v[166:169], v[204:207], v[86:89]
	v_mfma_f32_16x16x32_bf16 v[78:81], v[174:177], v[204:207], v[78:81]
	v_mfma_f32_16x16x32_bf16 v[70:73], v[166:169], v[212:215], v[70:73]
	v_mfma_f32_16x16x32_bf16 v[66:69], v[174:177], v[212:215], v[66:69]
	s_barrier
	s_setprio 0
	s_add_i32 s1, s56, s39
	v_lshl_add_u64 v[140:141], s[28:29], 0, v[186:187]
	s_mov_b32 m0, s1
	ds_read_b128 v[178:181], v145 offset:16384
	ds_read_b128 v[182:185], v145 offset:17408
	ds_read_b128 v[192:195], v145 offset:18432
	ds_read_b128 v[196:199], v145 offset:19456
	ds_read_b128 v[200:203], v145 offset:20480
	ds_read_b128 v[204:207], v145 offset:21504
	ds_read_b128 v[208:211], v145 offset:22528
	ds_read_b128 v[212:215], v145 offset:23552
	global_load_lds_dwordx4 v[140:141], off
	s_add_i32 m0, s1, 0x2000
	s_add_u32 s56, s28, 0x80000
	v_lshl_add_u64 v[188:189], s[28:29], 0, v[130:131]
	s_addc_u32 s57, s29, 0
	s_add_i32 s0, s0, s39
	global_load_lds_dwordx4 v[188:189], off
	v_lshl_add_u64 v[216:217], s[56:57], 0, v[186:187]
	s_mov_b32 m0, s0
	v_lshl_add_u64 v[218:219], s[30:31], 0, v[132:133]
	global_load_lds_dwordx4 v[216:217], off
	v_lshl_add_u64 v[216:217], s[56:57], 0, v[130:131]
	s_add_i32 m0, s0, 0x2000
	s_nop 0
	global_load_lds_dwordx4 v[216:217], off
	v_lshl_add_u64 v[216:217], s[30:31], 0, v[134:135]
	s_mov_b32 m0, s25
	s_nop 0
	global_load_lds_dwordx4 v[216:217], off
	s_mov_b32 m0, s40
	s_nop 0
	global_load_lds_dwordx4 v[218:219], off
	s_waitcnt vmcnt(8)
	s_waitcnt lgkmcnt(0)
	s_setprio 1
	s_barrier

	v_mfma_f32_16x16x32_bf16 v[62:65], v[146:149], v[178:181], v[62:65]
	v_mfma_f32_16x16x32_bf16 v[58:61], v[154:157], v[178:181], v[58:61]
	v_mfma_f32_16x16x32_bf16 v[50:53], v[146:149], v[192:195], v[50:53]
	v_mfma_f32_16x16x32_bf16 v[42:45], v[154:157], v[192:195], v[42:45]
	v_mfma_f32_16x16x32_bf16 v[34:37], v[146:149], v[200:203], v[34:37]
	v_mfma_f32_16x16x32_bf16 v[26:29], v[154:157], v[200:203], v[26:29]
	v_mfma_f32_16x16x32_bf16 v[18:21], v[146:149], v[208:211], v[18:21]
	v_mfma_f32_16x16x32_bf16 v[10:13], v[154:157], v[208:211], v[10:13]
	v_mfma_f32_16x16x32_bf16 v[62:65], v[150:153], v[182:185], v[62:65]
	v_mfma_f32_16x16x32_bf16 v[58:61], v[158:161], v[182:185], v[58:61]
	v_mfma_f32_16x16x32_bf16 v[50:53], v[150:153], v[196:199], v[50:53]
	v_mfma_f32_16x16x32_bf16 v[42:45], v[158:161], v[196:199], v[42:45]
	v_mfma_f32_16x16x32_bf16 v[34:37], v[150:153], v[204:207], v[34:37]
	v_mfma_f32_16x16x32_bf16 v[26:29], v[158:161], v[204:207], v[26:29]
	v_mfma_f32_16x16x32_bf16 v[18:21], v[150:153], v[212:215], v[18:21]
	v_mfma_f32_16x16x32_bf16 v[10:13], v[158:161], v[212:215], v[10:13]


	v_mfma_f32_16x16x32_bf16 v[54:57], v[162:165], v[178:181], v[54:57]
	v_mfma_f32_16x16x32_bf16 v[46:49], v[170:173], v[178:181], v[46:49]
	v_mfma_f32_16x16x32_bf16 v[38:41], v[162:165], v[192:195], v[38:41]
	v_mfma_f32_16x16x32_bf16 v[30:33], v[170:173], v[192:195], v[30:33]
	v_mfma_f32_16x16x32_bf16 v[22:25], v[162:165], v[200:203], v[22:25]
	v_mfma_f32_16x16x32_bf16 v[14:17], v[170:173], v[200:203], v[14:17]
	v_mfma_f32_16x16x32_bf16 v[6:9], v[162:165], v[208:211], v[6:9]
	v_mfma_f32_16x16x32_bf16 v[2:5], v[170:173], v[208:211], v[2:5]
	v_mfma_f32_16x16x32_bf16 v[54:57], v[166:169], v[182:185], v[54:57]
	v_mfma_f32_16x16x32_bf16 v[46:49], v[174:177], v[182:185], v[46:49]
	v_mfma_f32_16x16x32_bf16 v[38:41], v[166:169], v[196:199], v[38:41]
	v_mfma_f32_16x16x32_bf16 v[30:33], v[174:177], v[196:199], v[30:33]
	v_mfma_f32_16x16x32_bf16 v[22:25], v[166:169], v[204:207], v[22:25]
	v_mfma_f32_16x16x32_bf16 v[14:17], v[174:177], v[204:207], v[14:17]
	v_mfma_f32_16x16x32_bf16 v[6:9], v[166:169], v[212:215], v[6:9]
	v_mfma_f32_16x16x32_bf16 v[2:5], v[174:177], v[212:215], v[2:5]
	s_barrier
	s_setprio 0
	s_add_i32 s0, 0, 0x18000
	s_add_i32 s1, 0, 0x1c000
	v_add_u32_e32 v158, s0, v144
	v_add_u32_e32 v174, s1, v144
	ds_read_b128 v[146:149], v158
	ds_read_b128 v[150:153], v158 offset:1024
	ds_read_b128 v[154:157], v158 offset:2048
	ds_read_b128 v[158:161], v158 offset:3072
	ds_read_b128 v[162:165], v174
	ds_read_b128 v[166:169], v174 offset:1024
	ds_read_b128 v[170:173], v174 offset:2048
	ds_read_b128 v[174:177], v174 offset:3072
	s_add_u32 s30, s30, 0x80000
	s_addc_u32 s31, s31, 0
	s_mov_b32 m0, s41
	v_lshl_add_u64 v[220:221], s[30:31], 0, v[134:135]
	ds_read_b128 v[178:181], v145 offset:32768
	ds_read_b128 v[182:185], v145 offset:33792
	ds_read_b128 v[192:195], v145 offset:34816
	ds_read_b128 v[196:199], v145 offset:35840
	ds_read_b128 v[200:203], v145 offset:36864
	ds_read_b128 v[204:207], v145 offset:37888
	ds_read_b128 v[208:211], v145 offset:38912
	ds_read_b128 v[212:215], v145 offset:39936
	global_load_lds_dwordx4 v[220:221], off
	v_lshl_add_u64 v[220:221], s[30:31], 0, v[132:133]
	s_mov_b32 m0, s42
	s_nop 0
	global_load_lds_dwordx4 v[220:221], off
	s_waitcnt vmcnt(8)
	s_waitcnt lgkmcnt(0)
	s_setprio 1
	s_barrier

	v_mfma_f32_16x16x32_bf16 v[126:129], v[146:149], v[178:181], v[126:129]
	v_mfma_f32_16x16x32_bf16 v[122:125], v[154:157], v[178:181], v[122:125]
	v_mfma_f32_16x16x32_bf16 v[114:117], v[146:149], v[192:195], v[114:117]
	v_mfma_f32_16x16x32_bf16 v[106:109], v[154:157], v[192:195], v[106:109]
	v_mfma_f32_16x16x32_bf16 v[98:101], v[146:149], v[200:203], v[98:101]
	v_mfma_f32_16x16x32_bf16 v[90:93], v[154:157], v[200:203], v[90:93]
	v_mfma_f32_16x16x32_bf16 v[82:85], v[146:149], v[208:211], v[82:85]
	v_mfma_f32_16x16x32_bf16 v[74:77], v[154:157], v[208:211], v[74:77]
	v_mfma_f32_16x16x32_bf16 v[126:129], v[150:153], v[182:185], v[126:129]
	v_mfma_f32_16x16x32_bf16 v[122:125], v[158:161], v[182:185], v[122:125]
	v_mfma_f32_16x16x32_bf16 v[114:117], v[150:153], v[196:199], v[114:117]
	v_mfma_f32_16x16x32_bf16 v[106:109], v[158:161], v[196:199], v[106:109]
	v_mfma_f32_16x16x32_bf16 v[98:101], v[150:153], v[204:207], v[98:101]
	v_mfma_f32_16x16x32_bf16 v[90:93], v[158:161], v[204:207], v[90:93]
	v_mfma_f32_16x16x32_bf16 v[82:85], v[150:153], v[212:215], v[82:85]
	v_mfma_f32_16x16x32_bf16 v[74:77], v[158:161], v[212:215], v[74:77]


	v_mfma_f32_16x16x32_bf16 v[118:121], v[162:165], v[178:181], v[118:121]
	v_mfma_f32_16x16x32_bf16 v[110:113], v[170:173], v[178:181], v[110:113]
	v_mfma_f32_16x16x32_bf16 v[102:105], v[162:165], v[192:195], v[102:105]
	v_mfma_f32_16x16x32_bf16 v[94:97], v[170:173], v[192:195], v[94:97]
	v_mfma_f32_16x16x32_bf16 v[86:89], v[162:165], v[200:203], v[86:89]
	v_mfma_f32_16x16x32_bf16 v[78:81], v[170:173], v[200:203], v[78:81]
	v_mfma_f32_16x16x32_bf16 v[70:73], v[162:165], v[208:211], v[70:73]
	v_mfma_f32_16x16x32_bf16 v[66:69], v[170:173], v[208:211], v[66:69]
	v_mfma_f32_16x16x32_bf16 v[118:121], v[166:169], v[182:185], v[118:121]
	v_mfma_f32_16x16x32_bf16 v[110:113], v[174:177], v[182:185], v[110:113]
	v_mfma_f32_16x16x32_bf16 v[102:105], v[166:169], v[196:199], v[102:105]
	v_mfma_f32_16x16x32_bf16 v[94:97], v[174:177], v[196:199], v[94:97]
	v_mfma_f32_16x16x32_bf16 v[86:89], v[166:169], v[204:207], v[86:89]
	v_mfma_f32_16x16x32_bf16 v[78:81], v[174:177], v[204:207], v[78:81]
	v_mfma_f32_16x16x32_bf16 v[70:73], v[166:169], v[212:215], v[70:73]
	v_mfma_f32_16x16x32_bf16 v[66:69], v[174:177], v[212:215], v[66:69]
	s_barrier
	s_setprio 0
	s_add_i32 s0, s0, s39
	v_lshl_add_u64 v[140:141], v[140:141], 0, s[84:85]
	s_mov_b32 m0, s0
	ds_read_b128 v[178:181], v145 offset:49152
	ds_read_b128 v[182:185], v145 offset:50176
	ds_read_b128 v[192:195], v145 offset:51200
	ds_read_b128 v[196:199], v145 offset:52224
	ds_read_b128 v[200:203], v145 offset:53248
	ds_read_b128 v[204:207], v145 offset:54272
	ds_read_b128 v[208:211], v145 offset:55296
	ds_read_b128 v[212:215], v145 offset:56320
	global_load_lds_dwordx4 v[140:141], off
	s_add_i32 m0, s0, 0x2000
	s_add_u32 s28, s28, 0x80080
	v_lshl_add_u64 v[140:141], v[188:189], 0, s[84:85]
	s_addc_u32 s29, s29, 0
	s_add_i32 s0, s1, s39
	global_load_lds_dwordx4 v[140:141], off
	v_lshl_add_u64 v[140:141], s[28:29], 0, v[186:187]
	s_mov_b32 m0, s0
	s_nop 0
	global_load_lds_dwordx4 v[140:141], off
	v_lshl_add_u64 v[140:141], s[28:29], 0, v[130:131]
	s_add_i32 m0, s0, 0x2000
	s_nop 0
	global_load_lds_dwordx4 v[140:141], off
	v_lshl_add_u64 v[140:141], v[216:217], 0, s[84:85]
	s_mov_b32 m0, s43
	s_nop 0
	global_load_lds_dwordx4 v[140:141], off
	v_lshl_add_u64 v[140:141], v[218:219], 0, s[84:85]
	s_mov_b32 m0, s44
	s_nop 0
	global_load_lds_dwordx4 v[140:141], off
	s_waitcnt vmcnt(8)
	s_waitcnt lgkmcnt(0)
	s_setprio 1
	s_barrier

	v_mfma_f32_16x16x32_bf16 v[62:65], v[146:149], v[178:181], v[62:65]
	v_mfma_f32_16x16x32_bf16 v[58:61], v[154:157], v[178:181], v[58:61]
	v_mfma_f32_16x16x32_bf16 v[50:53], v[146:149], v[192:195], v[50:53]
	v_mfma_f32_16x16x32_bf16 v[42:45], v[154:157], v[192:195], v[42:45]
	v_mfma_f32_16x16x32_bf16 v[34:37], v[146:149], v[200:203], v[34:37]
	v_mfma_f32_16x16x32_bf16 v[26:29], v[154:157], v[200:203], v[26:29]
	v_mfma_f32_16x16x32_bf16 v[18:21], v[146:149], v[208:211], v[18:21]
	v_mfma_f32_16x16x32_bf16 v[10:13], v[154:157], v[208:211], v[10:13]
	v_mfma_f32_16x16x32_bf16 v[62:65], v[150:153], v[182:185], v[62:65]
	v_mfma_f32_16x16x32_bf16 v[58:61], v[158:161], v[182:185], v[58:61]
	v_mfma_f32_16x16x32_bf16 v[50:53], v[150:153], v[196:199], v[50:53]
	v_mfma_f32_16x16x32_bf16 v[42:45], v[158:161], v[196:199], v[42:45]
	v_mfma_f32_16x16x32_bf16 v[34:37], v[150:153], v[204:207], v[34:37]
	v_mfma_f32_16x16x32_bf16 v[26:29], v[158:161], v[204:207], v[26:29]
	v_mfma_f32_16x16x32_bf16 v[18:21], v[150:153], v[212:215], v[18:21]
	v_mfma_f32_16x16x32_bf16 v[10:13], v[158:161], v[212:215], v[10:13]


	v_mfma_f32_16x16x32_bf16 v[54:57], v[162:165], v[178:181], v[54:57]
	v_mfma_f32_16x16x32_bf16 v[46:49], v[170:173], v[178:181], v[46:49]
	v_mfma_f32_16x16x32_bf16 v[38:41], v[162:165], v[192:195], v[38:41]
	v_mfma_f32_16x16x32_bf16 v[30:33], v[170:173], v[192:195], v[30:33]
	v_mfma_f32_16x16x32_bf16 v[22:25], v[162:165], v[200:203], v[22:25]
	v_mfma_f32_16x16x32_bf16 v[14:17], v[170:173], v[200:203], v[14:17]
	v_mfma_f32_16x16x32_bf16 v[6:9], v[162:165], v[208:211], v[6:9]
	v_mfma_f32_16x16x32_bf16 v[2:5], v[170:173], v[208:211], v[2:5]
	v_mfma_f32_16x16x32_bf16 v[54:57], v[166:169], v[182:185], v[54:57]
	v_mfma_f32_16x16x32_bf16 v[46:49], v[174:177], v[182:185], v[46:49]
	v_mfma_f32_16x16x32_bf16 v[38:41], v[166:169], v[196:199], v[38:41]
	v_mfma_f32_16x16x32_bf16 v[30:33], v[174:177], v[196:199], v[30:33]
	v_mfma_f32_16x16x32_bf16 v[22:25], v[166:169], v[204:207], v[22:25]
	v_mfma_f32_16x16x32_bf16 v[14:17], v[174:177], v[204:207], v[14:17]
	v_mfma_f32_16x16x32_bf16 v[6:9], v[166:169], v[212:215], v[6:9]
	v_mfma_f32_16x16x32_bf16 v[2:5], v[174:177], v[212:215], v[2:5]
	s_barrier
	s_setprio 0
	s_add_i32 s55, s55, 2
	s_add_u32 s26, s26, 0x100
	s_addc_u32 s27, s27, 0
	s_add_u32 s53, s53, 0x100
	s_addc_u32 s54, s54, 0
	s_cmp_gt_u32 s55, 29
	s_cbranch_scc0 .LBB0_443
	s_and_b64 vcc, exec, s[14:15]
	s_cbranch_vccz .LBB0_446
	s_barrier

.LBB0_1126:
	s_add_u32 s0, s28, 0xfff80080
	s_addc_u32 s1, s29, -1
	s_add_i32 s54, 0, 0x10000
	s_cmp_eq_u32 s53, 28
	s_cselect_b32 s35, s19, s1
	s_cselect_b32 s34, s25, s0
	s_cselect_b32 s31, s17, s52
	s_cselect_b32 s30, s27, s51
	s_add_i32 s55, 0, 0x14000
	v_add_u32_e32 v126, s54, v237
	v_add_u32_e32 v158, s55, v237
	ds_read_b128 v[90:93], v126
	ds_read_b128 v[102:105], v126 offset:1024
	ds_read_b128 v[114:117], v126 offset:2048
	ds_read_b128 v[126:129], v126 offset:3072
	ds_read_b128 v[138:141], v158
	ds_read_b128 v[142:145], v158 offset:1024
	ds_read_b128 v[154:157], v158 offset:2048
	ds_read_b128 v[158:161], v158 offset:3072
	v_lshl_add_u64 v[188:189], s[28:29], 0, v[198:199]
	s_add_i32 m0, s40, 0xc000
	ds_read_b128 v[162:165], v238
	ds_read_b128 v[166:169], v238 offset:1024
	ds_read_b128 v[170:173], v238 offset:2048
	ds_read_b128 v[174:177], v238 offset:3072
	ds_read_b128 v[178:181], v238 offset:4096
	ds_read_b128 v[182:185], v238 offset:5120
	ds_read_b128 v[202:205], v238 offset:6144
	ds_read_b128 v[206:209], v238 offset:7168
	global_load_lds_dwordx4 v[188:189], off
	v_lshl_add_u64 v[188:189], s[28:29], 0, v[200:201]
	s_add_i32 m0, s40, 0xe000
	s_nop 0
	global_load_lds_dwordx4 v[188:189], off
	s_waitcnt vmcnt(8)
	s_waitcnt lgkmcnt(0)
	s_setprio 1
	s_barrier

	v_mfma_f32_16x16x32_bf16 v[150:153], v[90:93], v[162:165], v[150:153]
	v_mfma_f32_16x16x32_bf16 v[146:149], v[114:117], v[162:165], v[146:149]
	v_mfma_f32_16x16x32_bf16 v[122:125], v[90:93], v[170:173], v[122:125]
	v_mfma_f32_16x16x32_bf16 v[118:121], v[114:117], v[170:173], v[118:121]
	v_mfma_f32_16x16x32_bf16 v[98:101], v[90:93], v[178:181], v[98:101]
	v_mfma_f32_16x16x32_bf16 v[94:97], v[114:117], v[178:181], v[94:97]
	v_mfma_f32_16x16x32_bf16 v[78:81], v[90:93], v[202:205], v[78:81]
	v_mfma_f32_16x16x32_bf16 v[74:77], v[114:117], v[202:205], v[74:77]
	v_mfma_f32_16x16x32_bf16 v[150:153], v[102:105], v[166:169], v[150:153]
	v_mfma_f32_16x16x32_bf16 v[146:149], v[126:129], v[166:169], v[146:149]
	v_mfma_f32_16x16x32_bf16 v[122:125], v[102:105], v[174:177], v[122:125]
	v_mfma_f32_16x16x32_bf16 v[118:121], v[126:129], v[174:177], v[118:121]
	v_mfma_f32_16x16x32_bf16 v[98:101], v[102:105], v[182:185], v[98:101]
	v_mfma_f32_16x16x32_bf16 v[94:97], v[126:129], v[182:185], v[94:97]
	v_mfma_f32_16x16x32_bf16 v[78:81], v[102:105], v[206:209], v[78:81]
	v_mfma_f32_16x16x32_bf16 v[74:77], v[126:129], v[206:209], v[74:77]


	v_mfma_f32_16x16x32_bf16 v[134:137], v[138:141], v[162:165], v[134:137]
	v_mfma_f32_16x16x32_bf16 v[130:133], v[154:157], v[162:165], v[130:133]
	v_mfma_f32_16x16x32_bf16 v[110:113], v[138:141], v[170:173], v[110:113]
	v_mfma_f32_16x16x32_bf16 v[106:109], v[154:157], v[170:173], v[106:109]
	v_mfma_f32_16x16x32_bf16 v[86:89], v[138:141], v[178:181], v[86:89]
	v_mfma_f32_16x16x32_bf16 v[82:85], v[154:157], v[178:181], v[82:85]
	v_mfma_f32_16x16x32_bf16 v[70:73], v[138:141], v[202:205], v[70:73]
	v_mfma_f32_16x16x32_bf16 v[66:69], v[154:157], v[202:205], v[66:69]
	v_mfma_f32_16x16x32_bf16 v[134:137], v[142:145], v[166:169], v[134:137]
	v_mfma_f32_16x16x32_bf16 v[130:133], v[158:161], v[166:169], v[130:133]
	v_mfma_f32_16x16x32_bf16 v[110:113], v[142:145], v[174:177], v[110:113]
	v_mfma_f32_16x16x32_bf16 v[106:109], v[158:161], v[174:177], v[106:109]
	v_mfma_f32_16x16x32_bf16 v[86:89], v[142:145], v[182:185], v[86:89]
	v_mfma_f32_16x16x32_bf16 v[82:85], v[158:161], v[182:185], v[82:85]
	v_mfma_f32_16x16x32_bf16 v[70:73], v[142:145], v[206:209], v[70:73]
	v_mfma_f32_16x16x32_bf16 v[66:69], v[158:161], v[206:209], v[66:69]
	s_barrier
	s_setprio 0
	s_add_i32 s0, s54, s39
	v_lshl_add_u64 v[188:189], s[30:31], 0, v[186:187]
	s_mov_b32 m0, s0
	ds_read_b128 v[162:165], v238 offset:16384
	ds_read_b128 v[166:169], v238 offset:17408
	ds_read_b128 v[170:173], v238 offset:18432
	ds_read_b128 v[174:177], v238 offset:19456
	ds_read_b128 v[178:181], v238 offset:20480
	ds_read_b128 v[182:185], v238 offset:21504
	ds_read_b128 v[202:205], v238 offset:22528
	ds_read_b128 v[206:209], v238 offset:23552
	global_load_lds_dwordx4 v[188:189], off
	s_add_i32 m0, s0, 0x2000
	s_add_u32 s0, s30, 0x80000
	v_lshl_add_u64 v[210:211], s[30:31], 0, v[196:197]
	s_addc_u32 s1, s31, 0
	s_add_i32 s54, s55, s39
	global_load_lds_dwordx4 v[210:211], off
	v_lshl_add_u64 v[212:213], s[0:1], 0, v[186:187]
	s_mov_b32 m0, s54
	v_lshl_add_u64 v[214:215], s[34:35], 0, v[194:195]
	global_load_lds_dwordx4 v[212:213], off
	v_lshl_add_u64 v[212:213], s[0:1], 0, v[196:197]
	s_add_i32 m0, s54, 0x2000
	s_nop 0
	global_load_lds_dwordx4 v[212:213], off
	v_lshl_add_u64 v[212:213], s[34:35], 0, v[192:193]
	s_mov_b32 m0, s40
	s_nop 0
	global_load_lds_dwordx4 v[212:213], off
	s_mov_b32 m0, s41
	s_nop 0
	global_load_lds_dwordx4 v[214:215], off
	s_waitcnt vmcnt(8)
	s_waitcnt lgkmcnt(0)
	s_setprio 1
	s_barrier

	v_mfma_f32_16x16x32_bf16 v[62:65], v[90:93], v[162:165], v[62:65]
	v_mfma_f32_16x16x32_bf16 v[58:61], v[114:117], v[162:165], v[58:61]
	v_mfma_f32_16x16x32_bf16 v[46:49], v[90:93], v[170:173], v[46:49]
	v_mfma_f32_16x16x32_bf16 v[42:45], v[114:117], v[170:173], v[42:45]
	v_mfma_f32_16x16x32_bf16 v[30:33], v[90:93], v[178:181], v[30:33]
	v_mfma_f32_16x16x32_bf16 v[26:29], v[114:117], v[178:181], v[26:29]
	v_mfma_f32_16x16x32_bf16 v[14:17], v[90:93], v[202:205], v[14:17]
	v_mfma_f32_16x16x32_bf16 v[10:13], v[114:117], v[202:205], v[10:13]
	v_mfma_f32_16x16x32_bf16 v[62:65], v[102:105], v[166:169], v[62:65]
	v_mfma_f32_16x16x32_bf16 v[58:61], v[126:129], v[166:169], v[58:61]
	v_mfma_f32_16x16x32_bf16 v[46:49], v[102:105], v[174:177], v[46:49]
	v_mfma_f32_16x16x32_bf16 v[42:45], v[126:129], v[174:177], v[42:45]
	v_mfma_f32_16x16x32_bf16 v[30:33], v[102:105], v[182:185], v[30:33]
	v_mfma_f32_16x16x32_bf16 v[26:29], v[126:129], v[182:185], v[26:29]
	v_mfma_f32_16x16x32_bf16 v[14:17], v[102:105], v[206:209], v[14:17]
	v_mfma_f32_16x16x32_bf16 v[10:13], v[126:129], v[206:209], v[10:13]


	v_mfma_f32_16x16x32_bf16 v[54:57], v[138:141], v[162:165], v[54:57]
	v_mfma_f32_16x16x32_bf16 v[50:53], v[154:157], v[162:165], v[50:53]
	v_mfma_f32_16x16x32_bf16 v[38:41], v[138:141], v[170:173], v[38:41]
	v_mfma_f32_16x16x32_bf16 v[34:37], v[154:157], v[170:173], v[34:37]
	v_mfma_f32_16x16x32_bf16 v[22:25], v[138:141], v[178:181], v[22:25]
	v_mfma_f32_16x16x32_bf16 v[18:21], v[154:157], v[178:181], v[18:21]
	v_mfma_f32_16x16x32_bf16 v[6:9], v[138:141], v[202:205], v[6:9]
	v_mfma_f32_16x16x32_bf16 v[2:5], v[154:157], v[202:205], v[2:5]
	v_mfma_f32_16x16x32_bf16 v[54:57], v[142:145], v[166:169], v[54:57]
	v_mfma_f32_16x16x32_bf16 v[50:53], v[158:161], v[166:169], v[50:53]
	v_mfma_f32_16x16x32_bf16 v[38:41], v[142:145], v[174:177], v[38:41]
	v_mfma_f32_16x16x32_bf16 v[34:37], v[158:161], v[174:177], v[34:37]
	v_mfma_f32_16x16x32_bf16 v[22:25], v[142:145], v[182:185], v[22:25]
	v_mfma_f32_16x16x32_bf16 v[18:21], v[158:161], v[182:185], v[18:21]
	v_mfma_f32_16x16x32_bf16 v[6:9], v[142:145], v[206:209], v[6:9]
	v_mfma_f32_16x16x32_bf16 v[2:5], v[158:161], v[206:209], v[2:5]
	s_barrier
	s_setprio 0
	s_add_i32 s54, 0, 0x18000
	s_add_i32 s55, 0, 0x1c000
	v_add_u32_e32 v126, s54, v237
	v_add_u32_e32 v158, s55, v237
	ds_read_b128 v[90:93], v126
	ds_read_b128 v[102:105], v126 offset:1024
	ds_read_b128 v[114:117], v126 offset:2048
	ds_read_b128 v[126:129], v126 offset:3072
	ds_read_b128 v[138:141], v158
	ds_read_b128 v[142:145], v158 offset:1024
	ds_read_b128 v[154:157], v158 offset:2048
	ds_read_b128 v[158:161], v158 offset:3072
	s_add_u32 s0, s34, 0x80000
	s_addc_u32 s1, s35, 0
	s_mov_b32 m0, s42
	v_lshl_add_u64 v[216:217], s[0:1], 0, v[192:193]
	ds_read_b128 v[162:165], v238 offset:32768
	ds_read_b128 v[166:169], v238 offset:33792
	ds_read_b128 v[170:173], v238 offset:34816
	ds_read_b128 v[174:177], v238 offset:35840
	ds_read_b128 v[178:181], v238 offset:36864
	ds_read_b128 v[182:185], v238 offset:37888
	ds_read_b128 v[202:205], v238 offset:38912
	ds_read_b128 v[206:209], v238 offset:39936
	global_load_lds_dwordx4 v[216:217], off
	v_lshl_add_u64 v[216:217], s[0:1], 0, v[194:195]
	s_mov_b32 m0, s43
	s_nop 0
	global_load_lds_dwordx4 v[216:217], off
	s_waitcnt vmcnt(8)
	s_waitcnt lgkmcnt(0)
	s_setprio 1
	s_barrier

	v_mfma_f32_16x16x32_bf16 v[150:153], v[90:93], v[162:165], v[150:153]
	v_mfma_f32_16x16x32_bf16 v[146:149], v[114:117], v[162:165], v[146:149]
	v_mfma_f32_16x16x32_bf16 v[122:125], v[90:93], v[170:173], v[122:125]
	v_mfma_f32_16x16x32_bf16 v[118:121], v[114:117], v[170:173], v[118:121]
	v_mfma_f32_16x16x32_bf16 v[98:101], v[90:93], v[178:181], v[98:101]
	v_mfma_f32_16x16x32_bf16 v[94:97], v[114:117], v[178:181], v[94:97]
	v_mfma_f32_16x16x32_bf16 v[78:81], v[90:93], v[202:205], v[78:81]
	v_mfma_f32_16x16x32_bf16 v[74:77], v[114:117], v[202:205], v[74:77]
	v_mfma_f32_16x16x32_bf16 v[150:153], v[102:105], v[166:169], v[150:153]
	v_mfma_f32_16x16x32_bf16 v[146:149], v[126:129], v[166:169], v[146:149]
	v_mfma_f32_16x16x32_bf16 v[122:125], v[102:105], v[174:177], v[122:125]
	v_mfma_f32_16x16x32_bf16 v[118:121], v[126:129], v[174:177], v[118:121]
	v_mfma_f32_16x16x32_bf16 v[98:101], v[102:105], v[182:185], v[98:101]
	v_mfma_f32_16x16x32_bf16 v[94:97], v[126:129], v[182:185], v[94:97]
	v_mfma_f32_16x16x32_bf16 v[78:81], v[102:105], v[206:209], v[78:81]
	v_mfma_f32_16x16x32_bf16 v[74:77], v[126:129], v[206:209], v[74:77]


	v_mfma_f32_16x16x32_bf16 v[134:137], v[138:141], v[162:165], v[134:137]
	v_mfma_f32_16x16x32_bf16 v[130:133], v[154:157], v[162:165], v[130:133]
	v_mfma_f32_16x16x32_bf16 v[110:113], v[138:141], v[170:173], v[110:113]
	v_mfma_f32_16x16x32_bf16 v[106:109], v[154:157], v[170:173], v[106:109]
	v_mfma_f32_16x16x32_bf16 v[86:89], v[138:141], v[178:181], v[86:89]
	v_mfma_f32_16x16x32_bf16 v[82:85], v[154:157], v[178:181], v[82:85]
	v_mfma_f32_16x16x32_bf16 v[70:73], v[138:141], v[202:205], v[70:73]
	v_mfma_f32_16x16x32_bf16 v[66:69], v[154:157], v[202:205], v[66:69]
	v_mfma_f32_16x16x32_bf16 v[134:137], v[142:145], v[166:169], v[134:137]
	v_mfma_f32_16x16x32_bf16 v[130:133], v[158:161], v[166:169], v[130:133]
	v_mfma_f32_16x16x32_bf16 v[110:113], v[142:145], v[174:177], v[110:113]
	v_mfma_f32_16x16x32_bf16 v[106:109], v[158:161], v[174:177], v[106:109]
	v_mfma_f32_16x16x32_bf16 v[86:89], v[142:145], v[182:185], v[86:89]
	v_mfma_f32_16x16x32_bf16 v[82:85], v[158:161], v[182:185], v[82:85]
	v_mfma_f32_16x16x32_bf16 v[70:73], v[142:145], v[206:209], v[70:73]
	v_mfma_f32_16x16x32_bf16 v[66:69], v[158:161], v[206:209], v[66:69]
	s_barrier
	s_setprio 0
	s_add_i32 s0, s54, s39
	v_lshl_add_u64 v[188:189], v[188:189], 0, s[84:85]
	s_mov_b32 m0, s0
	ds_read_b128 v[162:165], v238 offset:49152
	ds_read_b128 v[166:169], v238 offset:50176
	ds_read_b128 v[170:173], v238 offset:51200
	ds_read_b128 v[174:177], v238 offset:52224
	ds_read_b128 v[178:181], v238 offset:53248
	ds_read_b128 v[182:185], v238 offset:54272
	ds_read_b128 v[202:205], v238 offset:55296
	ds_read_b128 v[206:209], v238 offset:56320
	global_load_lds_dwordx4 v[188:189], off
	s_add_i32 m0, s0, 0x2000
	s_add_u32 s0, s30, 0x80080
	v_lshl_add_u64 v[188:189], v[210:211], 0, s[84:85]
	s_addc_u32 s1, s31, 0
	s_add_i32 s30, s55, s39
	global_load_lds_dwordx4 v[188:189], off
	v_lshl_add_u64 v[188:189], s[0:1], 0, v[186:187]
	s_mov_b32 m0, s30
	s_nop 0
	global_load_lds_dwordx4 v[188:189], off
	v_lshl_add_u64 v[188:189], s[0:1], 0, v[196:197]
	s_add_i32 m0, s30, 0x2000
	s_nop 0
	global_load_lds_dwordx4 v[188:189], off
	v_lshl_add_u64 v[188:189], v[212:213], 0, s[84:85]
	s_mov_b32 m0, s47
	s_nop 0
	global_load_lds_dwordx4 v[188:189], off
	v_lshl_add_u64 v[188:189], v[214:215], 0, s[84:85]
	s_mov_b32 m0, s48
	s_nop 0
	global_load_lds_dwordx4 v[188:189], off
	s_waitcnt vmcnt(8)
	s_waitcnt lgkmcnt(0)
	s_setprio 1
	s_barrier

	v_mfma_f32_16x16x32_bf16 v[62:65], v[90:93], v[162:165], v[62:65]
	v_mfma_f32_16x16x32_bf16 v[58:61], v[114:117], v[162:165], v[58:61]
	v_mfma_f32_16x16x32_bf16 v[46:49], v[90:93], v[170:173], v[46:49]
	v_mfma_f32_16x16x32_bf16 v[42:45], v[114:117], v[170:173], v[42:45]
	v_mfma_f32_16x16x32_bf16 v[30:33], v[90:93], v[178:181], v[30:33]
	v_mfma_f32_16x16x32_bf16 v[26:29], v[114:117], v[178:181], v[26:29]
	v_mfma_f32_16x16x32_bf16 v[14:17], v[90:93], v[202:205], v[14:17]
	v_mfma_f32_16x16x32_bf16 v[10:13], v[114:117], v[202:205], v[10:13]
	v_mfma_f32_16x16x32_bf16 v[62:65], v[102:105], v[166:169], v[62:65]
	v_mfma_f32_16x16x32_bf16 v[58:61], v[126:129], v[166:169], v[58:61]
	v_mfma_f32_16x16x32_bf16 v[46:49], v[102:105], v[174:177], v[46:49]
	v_mfma_f32_16x16x32_bf16 v[42:45], v[126:129], v[174:177], v[42:45]
	v_mfma_f32_16x16x32_bf16 v[30:33], v[102:105], v[182:185], v[30:33]
	v_mfma_f32_16x16x32_bf16 v[26:29], v[126:129], v[182:185], v[26:29]
	v_mfma_f32_16x16x32_bf16 v[14:17], v[102:105], v[206:209], v[14:17]
	v_mfma_f32_16x16x32_bf16 v[10:13], v[126:129], v[206:209], v[10:13]


	v_mfma_f32_16x16x32_bf16 v[54:57], v[138:141], v[162:165], v[54:57]
	v_mfma_f32_16x16x32_bf16 v[50:53], v[154:157], v[162:165], v[50:53]
	v_mfma_f32_16x16x32_bf16 v[38:41], v[138:141], v[170:173], v[38:41]
	v_mfma_f32_16x16x32_bf16 v[34:37], v[154:157], v[170:173], v[34:37]
	v_mfma_f32_16x16x32_bf16 v[22:25], v[138:141], v[178:181], v[22:25]
	v_mfma_f32_16x16x32_bf16 v[18:21], v[154:157], v[178:181], v[18:21]
	v_mfma_f32_16x16x32_bf16 v[6:9], v[138:141], v[202:205], v[6:9]
	v_mfma_f32_16x16x32_bf16 v[2:5], v[154:157], v[202:205], v[2:5]
	v_mfma_f32_16x16x32_bf16 v[54:57], v[142:145], v[166:169], v[54:57]
	v_mfma_f32_16x16x32_bf16 v[50:53], v[158:161], v[166:169], v[50:53]
	v_mfma_f32_16x16x32_bf16 v[38:41], v[142:145], v[174:177], v[38:41]
	v_mfma_f32_16x16x32_bf16 v[34:37], v[158:161], v[174:177], v[34:37]
	v_mfma_f32_16x16x32_bf16 v[22:25], v[142:145], v[182:185], v[22:25]
	v_mfma_f32_16x16x32_bf16 v[18:21], v[158:161], v[182:185], v[18:21]
	v_mfma_f32_16x16x32_bf16 v[6:9], v[142:145], v[206:209], v[6:9]
	v_mfma_f32_16x16x32_bf16 v[2:5], v[158:161], v[206:209], v[2:5]
	s_barrier
	s_setprio 0
	s_add_i32 s53, s53, 2
	s_add_u32 s28, s28, 0x100
	s_addc_u32 s29, s29, 0
	s_add_u32 s51, s51, 0x100
	s_addc_u32 s52, s52, 0
	s_cmp_gt_u32 s53, 29
	s_cbranch_scc0 .LBB0_1126
	s_and_b64 vcc, exec, s[14:15]
	s_cbranch_vccz .LBB0_1129
	s_barrier
